# attention unit setup: K tiles, positional-key parts and first V tile loads issued back to back, one wait
# baseline (speedup 1.0000x reference)
.LBB0_1160:
	v_ashrrev_i32_e32 v0, 1, v144
	s_movk_i32 s4, 0xffe0
	v_bfe_u32 v132, v144, 5, 1
	v_bfi_b32 v133, s4, v0, v144
	v_mov_b64_e32 v[0:1], s[0:1]
	v_mad_i64_i32 v[0:1], s[0:1], v133, s50, v[0:1]
	v_lshlrev_b32_e32 v16, 4, v132
	v_mov_b32_e32 v17, v4
	v_lshl_add_u64 v[6:7], v[0:1], 0, v[16:17]
	global_load_dwordx4 v[96:99], v[6:7], off
	global_load_dwordx4 v[100:103], v[6:7], off offset:32
	global_load_dwordx4 v[104:107], v[6:7], off offset:64
	global_load_dwordx4 v[108:111], v[6:7], off offset:96
	v_ashrrev_i32_e32 v145, 31, v144
	v_lshl_add_u64 v[0:1], v[144:145], 4, s[12:13]
	global_load_dwordx4 v[80:83], v[0:1], off
	global_load_dwordx4 v[112:115], v[6:7], off offset:128
	global_load_dwordx4 v[116:119], v[6:7], off offset:160
	v_add_co_u32_e32 v0, vcc, 0x2000, v0
	v_lshlrev_b64 v[14:15], 3, v[144:145]
	s_movk_i32 s0, 0xff
	v_addc_co_u32_e32 v1, vcc, 0, v1, vcc
	global_load_dwordx4 v[88:91], v[0:1], off
	v_cmp_lt_i32_e64 s[0:1], s0, v144
	v_cmp_gt_i32_e64 s[4:5], s33, v144
	v_lshl_add_u64 v[8:9], v[14:15], 1, s[14:15]
	v_mov_b32_e32 v84, v4
	v_mov_b32_e32 v85, v4
	v_mov_b32_e32 v86, v4
	v_mov_b32_e32 v87, v4
	v_mov_b32_e32 v92, v4
	v_mov_b32_e32 v93, v4
	v_mov_b32_e32 v94, v4
	v_mov_b32_e32 v95, v4
	s_and_saveexec_b64 s[22:23], s[4:5]
	s_cbranch_execz .Latt_setup_nc
	global_load_dwordx4 v[84:87], v[8:9], off
	v_add_co_u32_e32 v8, vcc, 0x1000, v8
	s_nop 1
	v_addc_co_u32_e32 v9, vcc, 0, v9, vcc
	global_load_dwordx4 v[92:95], v[8:9], off
.Latt_setup_nc:
	s_or_b64 exec, exec, s[22:23]
	v_ashrrev_i32_e32 v17, 3, v144
	v_mad_i64_i32 v[0:1], s[22:23], s35, v17, 0
	v_lshlrev_b32_e32 v18, 4, v144
	v_lshl_add_u64 v[0:1], v[0:1], 1, s[20:21]
	v_and_b32_e32 v10, 0x70, v18
	v_mov_b32_e32 v11, v4
	v_lshl_add_u64 v[12:13], v[0:1], 0, v[10:11]
	global_load_dwordx4 v[120:123], v[12:13], off
	global_load_dwordx4 v[124:127], v[12:13], off offset:128
	s_movk_i32 s16, 0xd0
	v_mul_lo_u32 v0, v17, s16
	v_add_u32_e32 v1, 32, v0
	v_lshrrev_b32_e32 v2, 2, v144
	v_add_u32_e32 v134, v1, v10
	s_movk_i32 s51, 0xd0
	v_mul_lo_u32 v0, v2, s16
	v_and_b32_e32 v135, 48, v18
	s_waitcnt vmcnt(2)
	ds_write_b128 v134, v[80:83]
	s_and_saveexec_b64 s[22:23], s[0:1]
	s_xor_b64 s[0:1], exec, s[22:23]
	v_mul_lo_u32 v0, v2, s51
	v_and_b32_e32 v135, 48, v18
	s_andn2_saveexec_b64 s[0:1], s[0:1]
	v_add3_u32 v2, 32, v0, v135
	ds_write_b128 v2, v[84:87] offset:128
	s_or_b64 exec, exec, s[0:1]
	v_lshlrev_b32_e32 v3, 3, v144
	v_lshlrev_b32_e32 v5, 6, v17
	v_and_b32_e32 v3, 8, v3
	s_movk_i32 s0, 0x60
	v_sub_u32_e32 v1, v1, v5
	v_and_or_b32 v3, v18, s0, v3
	v_cmp_lt_i32_e32 vcc, v248, v242
	v_and_b32_e32 v2, 31, v144
	v_add_u32_e32 v136, v1, v3
	v_cndmask_b32_e32 v1, v241, v248, vcc
	v_mad_u32_u24 v18, v2, s51, 32
	v_lshlrev_b32_e32 v146, 2, v1
	v_lshlrev_b32_e32 v1, 6, v2
	v_add_u32_e32 v147, 32, v0
	v_and_b32_e32 v0, 7, v144
	v_sub_u32_e32 v19, v18, v1
	v_lshlrev_b32_e32 v0, 4, v0
	v_mov_b32_e32 v1, v4
	v_lshlrev_b32_e32 v2, 1, v17
	v_mad_i64_i32 v[0:1], s[0:1], v2, s35, v[0:1]
	v_lshl_add_u64 v[0:1], s[20:21], 0, v[0:1]
	v_mov_b32_e32 v14, v4
	v_mov_b32_e32 v15, v4
	v_lshlrev_b64 v[128:129], 4, v[144:145]
	v_lshl_add_u64 v[130:131], v[0:1], 0, s[96:97]
	v_mov_b32_e32 v0, v4
	v_mov_b32_e32 v1, v4
	v_mov_b32_e32 v2, v4
	v_mov_b32_e32 v3, v4
	v_mov_b32_e32 v5, v4
	v_mov_b32_e32 v6, v4
	v_mov_b32_e32 v7, v4
	v_mov_b32_e32 v8, v4
	v_mov_b32_e32 v9, v4
	v_mov_b32_e32 v10, v4
	v_mov_b32_e32 v11, v4
	v_mov_b32_e32 v12, v4
	v_mov_b32_e32 v13, v4
	v_add_u32_e32 v144, v18, v16
	v_add_u32_e32 v145, v19, v16
	v_mov_b64_e32 v[30:31], v[14:15]
	v_mov_b64_e32 v[46:47], v[14:15]
	s_lshr_b32 s16, s35, 6
	v_add_u32_e32 v137, 0x3000, v136
	v_mov_b32_e32 v182, 0x80000000
	v_mov_b32_e32 v183, v182
	v_mov_b32_e32 v184, v182
	v_mov_b32_e32 v185, v182
	v_mov_b32_e32 v186, v182
	v_mov_b32_e32 v187, v182
	v_mov_b32_e32 v188, v182
	v_mov_b32_e32 v189, v182
	v_mov_b32_e32 v190, v182
	v_mov_b32_e32 v191, v182
	v_mov_b32_e32 v192, v182
	v_mov_b32_e32 v193, v182
	v_mov_b32_e32 v194, v182
	v_mov_b32_e32 v195, v182
	v_mov_b32_e32 v196, v182
	v_mov_b32_e32 v197, v182
	v_mov_b32_e32 v148, 0
	s_mov_b32 s22, 3
	v_mov_b64_e32 v[28:29], v[12:13]
	v_mov_b64_e32 v[26:27], v[10:11]
	v_mov_b64_e32 v[24:25], v[8:9]
	v_mov_b64_e32 v[22:23], v[6:7]
	v_mov_b64_e32 v[20:21], v[4:5]
	v_mov_b64_e32 v[18:19], v[2:3]
	v_mov_b64_e32 v[16:17], v[0:1]
	v_mov_b64_e32 v[44:45], v[12:13]
	v_mov_b64_e32 v[42:43], v[10:11]
	v_mov_b64_e32 v[40:41], v[8:9]
	v_mov_b64_e32 v[38:39], v[6:7]
	v_mov_b64_e32 v[36:37], v[4:5]
	v_mov_b64_e32 v[34:35], v[2:3]
	v_mov_b64_e32 v[32:33], v[0:1]
	v_mov_b32_e32 v0, 0
	s_waitcnt vmcnt(1)
	ds_write2_b64 v137, v[120:121], v[122:123] offset0:128 offset1:130
	s_waitcnt lgkmcnt(0)
	s_barrier
	s_branch .LBB0_1171
